# v31: v25 + one static priority raise (s_setprio 1) for waves 4-7 over the two prompt-attention units, dropped after them (strategy: static priority for the younger half)
# speedup vs baseline: 1.0040x; 1.0040x over previous
.LBB0_1314:
	s_cmp_lg_u32 s62, 0
	s_cbranch_scc0 .Lattn_prio_done
	s_setprio 1

.LBB0_1595:
	s_setprio 0
	v_readlane_b32 s96, v238, 5
	v_readlane_b32 s64, v239, 51
	v_readlane_b32 s2, v238, 48
	v_readlane_b32 s92, v238, 38
	v_readlane_b32 s94, v238, 40
	v_readlane_b32 s87, v238, 4
	v_readlane_b32 s97, v238, 6
	v_readlane_b32 s84, v238, 7
	v_readlane_b32 s65, v239, 52
	v_readlane_b32 s68, v239, 55
	v_readlane_b32 s69, v239, 56
	v_readlane_b32 s76, v239, 63
	v_readlane_b32 s77, v238, 0
	v_readlane_b32 s3, v238, 49
	v_readlane_b32 s93, v238, 39
	v_readlane_b32 s95, v238, 41
	v_readlane_b32 s66, v239, 53
	v_readlane_b32 s67, v239, 54
	v_readlane_b32 s70, v239, 57
	v_readlane_b32 s71, v239, 58
	v_readlane_b32 s72, v239, 59
	v_readlane_b32 s73, v239, 60
	v_readlane_b32 s74, v239, 61
	v_readlane_b32 s75, v239, 62
	v_readlane_b32 s78, v238, 1
	v_readlane_b32 s79, v238, 2
	s_bitcmp1_b32 s94, 0
	s_cbranch_scc0 .LBB0_1596
	s_lshl_b32 s10, s94, 1
	s_branch .LBB0_1310
